# prologue de-serialisation: diff attention per-call prologue issues the tile-1 K/V loads together with the Q and tile-0 loads
# baseline (speedup 1.0000x reference)
; __device__ __forceinline__ int v_st(int k, int c) { const int kk = (k & ~0xC) | ((k & 4) << 1) | ((k & 8) >> 1); return ((kk >> 3) * 4 + (c >> 5)) * 512 + ((kk & 7) * 32 + (c & 31)) * 2; }
; __device__ __forceinline__ int v_rd_base(int lane) { return ((lane & 3) << 3) | (((lane >> 2) & 3) << 6) | (((lane >> 4) & 1) << 5) | (((lane >> 5) & 1) << 8); }
; #define SLOAD(i, j) do { const long rb_ = KROW(j); sr_[i].vs0 = *(const bf16x8*)(a.V + (rb_ + sr) * LDV + sc); sr_[i].vs1 = *(const bf16x8*)(a.V + (rb_ + 32 + sr) * LDV + sc); \
;     _Pragma("unroll") for (int c_ = 0; c_ < KCH; ++c_) sr_[i].ks[c_] = *(const bf16x8*)(kptr[c_] + rb_ * kld[c_]); } while (0)
; template <int DQK, int DK1, int LDQ, int LDK, int LDKR, int LDV, int NQL, int SDEPTH>
; __device__ __forceinline__ void attn_core(const AttnArgs& a, char* lds, f32x16 (&o)[4]) {
;     ...
;     char* QL = lds + 2 * SHM_V + 2 * SHM_K + 2048 + tid * 16;
;     { const bf16_t* Qw = a.Q + (long)(wid * 32 + r32) * LDQ + hi * 8;
; #pragma unroll
;       for (int d0 = 0; d0 < NQR; ++d0) qr[d0] = *(const bf16x8*)(Qw + d0 * 16);
; #pragma unroll
;       for (int d0 = NQR; d0 < ND0; ++d0) *(bf16x8*)(QL + (d0 - NQR) * 8192) = *(const bf16x8*)(Qw + d0 * 16); }
;     const int sr = tid >> 4, sc = (tid & 15) * 8, vst0 = v_st(sr, sc), vst1 = v_st(32 + sr, sc);
;     const int vb0 = (int)(uintptr_t)V_lds + v_rd_base(lane);
;     const bf16_t* kptr[KCH]; int kld[KCH], kwo[KCH];
; #pragma unroll
;     for (int c = 0; c < KCH; ++c) { const int idx = tid + c * 512, kr_ = idx / CPR, kc = (idx % CPR) * 8;
;         if (kc < DK1) { kptr[c] = a.Kn + (long)kr_ * LDK + kc; kld[c] = LDK; } else { kptr[c] = a.Kr + (long)kr_ * LDKR + (kc - DK1); kld[c] = LDKR; }
;         kwo[c] = kr_ * KP + ((kc * 2) ^ ((kr_ & 7) << 4)); }
;     struct { bf16x8 vs0, vs1, ks[KCH]; } sr_[SDEPTH];
;     int kb[4];
; #pragma unroll
;     for (int m = 0; m < 4; ++m) kb[m] = r32 * KP + ((m * 32 + hi * 16) ^ ((r32 & 7) << 4));
;     ...
;     f32x16 pA0, pA1, pB0, pB1; float mnA, mnB, alA, alB; bf16x8 pa0, pa1, pa2, pa3; const int NT = a.NT;
;     constexpr int SE = 0, SO = SDEPTH - 1;
;     SLOAD(SE, 0); asm volatile("s_waitcnt vmcnt(0)" ::: "memory"); SWRITE(0, SE); __syncthreads();
.LBB0_170:
	v_mov_b32_e32 v14, v159
	s_xor_b64 s[94:95], s[14:15], -1
	s_lshl_b64 s[14:15], s[12:13], 1
	s_add_u32 s12, s87, s14
	v_ashrrev_i32_e32 v0, 31, v14
	v_lshrrev_b32_e32 v0, 29, v0
	s_addc_u32 s13, s68, s15
	v_add_u32_e32 v0, v14, v0
	s_add_u32 s14, s28, s14
	v_ashrrev_i32_e32 v16, 3, v0
	v_and_b32_e32 v0, -8, v0
	s_addc_u32 s15, s29, s15
	v_sub_u32_e32 v17, v14, v0
	v_ashrrev_i32_e32 v164, 4, v14
	v_lshlrev_b32_e32 v0, 3, v17
	v_mov_b64_e32 v[2:3], s[14:15]
	v_mad_i64_i32 v[2:3], s[14:15], v16, s9, v[2:3]
	v_ashrrev_i32_e32 v1, 31, v0
	v_ashrrev_i32_e32 v165, 31, v164
	v_lshlrev_b32_e32 v15, 3, v14
	v_lshl_add_u64 v[166:167], v[0:1], 1, v[2:3]
	v_lshl_add_u64 v[0:1], v[164:165], 0, s[18:19]
	v_mov_b64_e32 v[50:51], s[20:21]
	v_and_b32_e32 v4, 0x78, v15
	v_mad_u64_u32 v[2:3], s[14:15], v0, s9, v[50:51]
	v_mad_i32_i24 v3, v1, s9, v3
	v_lshlrev_b32_e32 v48, 1, v4
	v_mov_b32_e32 v49, v97
	v_lshl_add_u64 v[168:169], v[164:165], 0, 32
	v_lshl_add_u64 v[0:1], v[2:3], 0, v[48:49]
	v_lshl_add_u64 v[2:3], v[168:169], 0, s[18:19]
	v_mad_u64_u32 v[4:5], s[14:15], v2, s9, v[50:51]
	v_mad_i32_i24 v5, v3, s9, v5
	v_lshl_add_u64 v[4:5], v[4:5], 0, v[48:49]
	global_load_dwordx4 v[0:3], v[0:1], off
	s_nop 0
	global_load_dwordx4 v[4:7], v[4:5], off
	v_ashrrev_i32_e32 v12, 1, v14
	v_lshl_add_u64 v[8:9], v[166:167], 0, s[22:23]
	v_bfi_b32 v18, s33, v12, v14
	v_mov_b64_e32 v[12:13], s[12:13]
	global_load_dwordx4 v[8:11], v[8:9], off
	v_mad_i64_i32 v[12:13], s[12:13], v18, s9, v[12:13]
	v_lshrrev_b32_e32 v18, 1, v14
	v_and_b32_e32 v96, 16, v18
	v_lshl_add_u64 v[12:13], v[12:13], 0, v[96:97]
	global_load_dwordx4 v[110:113], v[12:13], off
	global_load_dwordx4 v[106:109], v[12:13], off offset:32
	global_load_dwordx4 v[102:105], v[12:13], off offset:64
	global_load_dwordx4 v[98:101], v[12:13], off offset:96
	v_lshl_add_u64 v[240:241], v[164:165], 0, s[24:25]
	v_mad_u64_u32 v[242:243], vcc, v240, s9, v[50:51]
	v_lshl_add_u64 v[244:245], v[168:169], 0, s[24:25]
	v_mad_u64_u32 v[246:247], vcc, v244, s9, v[50:51]
	v_mad_i32_i24 v243, v241, s9, v243
	v_mad_i32_i24 v247, v245, s9, v247
	v_lshl_add_u64 v[240:241], v[242:243], 0, v[48:49]
	v_lshl_add_u64 v[244:245], v[246:247], 0, v[48:49]
	v_lshl_add_u64 v[248:249], v[166:167], 0, s[78:79]
	global_load_dwordx4 v[240:243], v[240:241], off
	s_nop 0
	global_load_dwordx4 v[244:247], v[244:245], off
	s_nop 0
	global_load_dwordx4 v[248:251], v[248:249], off
	v_and_b32_e32 v18, 0xfffff0, v164
	v_lshlrev_b32_e32 v19, 1, v164
	v_lshrrev_b32_e32 v20, 1, v164
	v_and_b32_e32 v21, 3, v164
	v_add_u32_e32 v22, 32, v164
	v_and_or_b32 v18, v19, 8, v18
	v_and_or_b32 v19, v20, 4, v21
	v_and_b32_e32 v20, 0xfffff0, v22
	v_lshlrev_b32_e32 v21, 1, v22
	v_bfe_u32 v15, v15, 5, 2
	v_lshrrev_b32_e32 v18, 1, v18
	v_and_or_b32 v20, v21, 8, v20
	v_and_b32_e32 v68, 31, v14
	v_lshlrev_b32_e32 v52, 4, v14
	v_or_b32_e32 v12, v18, v15
	v_lshrrev_b32_e32 v13, 1, v20
	v_lshlrev_b32_e32 v53, 7, v68
	v_and_b32_e32 v54, 0x70, v52
	v_and_b32_e32 v23, 48, v52
	v_lshlrev_b32_e32 v19, 6, v19
	v_lshlrev_b32_e32 v12, 9, v12
	v_or_b32_e32 v13, v13, v15
	v_bitop3_b32 v22, v96, v53, v54 bitop3:0xde
	v_lshlrev_b32_e32 v18, 7, v16
	v_bitop3_b32 v15, v16, v17, 7 bitop3:0x6c
	v_lshlrev_b32_e32 v13, 9, v13
	v_or3_b32 v12, v12, v19, v23
	v_lshl_add_u32 v15, v15, 4, v18
	v_or3_b32 v13, v13, v19, v23
	v_add_u32_e32 v181, 0, v12
	v_add_u32_e32 v186, 0, v22
	v_add_u32_e32 v182, 0, v15
	v_add_u32_e32 v184, 0, v13
	s_waitcnt vmcnt(0)
	v_and_b32_e32 v69, 63, v14
	v_lshl_add_u64 v[64:65], v[164:165], 0, s[88:89]
	v_mad_u64_u32 v[66:67], s[12:13], v64, s9, v[50:51]
	v_mad_i32_i24 v67, v65, s9, v67
	v_lshl_add_u64 v[60:61], v[166:167], 0, s[78:79]
	v_lshl_add_u64 v[64:65], v[66:67], 0, v[48:49]
	s_cmp_lg_u32 0, -1
	s_cselect_b32 s14, 0, 0
	s_waitcnt vmcnt(0)
	ds_write_b128 v181, v[0:3]
	s_waitcnt vmcnt(5)
	ds_write_b128 v184, v[4:7]
	s_waitcnt vmcnt(4)
	ds_write_b128 v182, v[8:11] offset:32768
	s_waitcnt lgkmcnt(0)
	s_barrier
; #define SLOAD(i, j) do { const long rb_ = KROW(j); sr_[i].vs0 = *(const bf16x8*)(a.V + (rb_ + sr) * LDV + sc); sr_[i].vs1 = *(const bf16x8*)(a.V + (rb_ + 32 + sr) * LDV + sc); \
;     _Pragma("unroll") for (int c_ = 0; c_ < KCH; ++c_) sr_[i].ks[c_] = *(const bf16x8*)(kptr[c_] + rb_ * kld[c_]); } while (0)
; #define SWRITE(b, i) do { *(bf16x8*)(V_lds + (b) * SHM_V + vst0) = sr_[i].vs0; *(bf16x8*)(V_lds + (b) * SHM_V + vst1) = sr_[i].vs1; \
;     _Pragma("unroll") for (int c_ = 0; c_ < KCH; ++c_) *(bf16x8*)(K_lds + (b) * SHM_K + kwo[c_]) = sr_[i].ks[c_]; } while (0)
; __device__ __forceinline__ void partialSM(f32x16& p0, f32x16& p1, float& m_reg, float& mn, float& alpha, const float C, const float thr) {
;     float pmax = p0[0];
; #pragma unroll
;     for (int r = 1; r < 16; ++r) pmax = fmaxf(pmax, p0[r]);
; #pragma unroll
;     for (int r = 0; r < 16; ++r) pmax = fmaxf(pmax, p1[r]);
;     { auto rr = __builtin_amdgcn_permlane32_swap(__float_as_uint(pmax), __float_as_uint(pmax), false, false);
;       pmax = fmaxf(__uint_as_float(rr[0]), __uint_as_float(rr[1])); }
;     if (__builtin_expect(__all(pmax - m_reg <= thr), 1)) { mn = m_reg; alpha = 1.f; }
;     else { mn = fmaxf(m_reg, pmax); alpha = __builtin_amdgcn_exp2f((m_reg - mn) * C); m_reg = mn; }
;     const float mnC = -mn * C;
; #pragma unroll
;     for (int r = 0; r < 16; ++r) p0[r] = fmaf(p0[r], C, mnC);
; #pragma unroll
;     for (int r = 0; r < 16; ++r) p1[r] = fmaf(p1[r], C, mnC);
; #pragma unroll
;     for (int r = 0; r < 16; ++r) p0[r] = __builtin_amdgcn_exp2f(p0[r]);
; template <int DQK, int DK1, int LDQ, int LDK, int LDKR, int LDV, int NQL, int SDEPTH>
; __device__ __forceinline__ void attn_core(const AttnArgs& a, char* lds, f32x16 (&o)[4]) {
;     ...
;     f32x16 pA0, pA1, pB0, pB1; float mnA, mnB, alA, alB; bf16x8 pa0, pa1, pa2, pa3; const int NT = a.NT;
;     constexpr int SE = 0, SO = SDEPTH - 1;
;     SLOAD(SE, 0); asm volatile("s_waitcnt vmcnt(0)" ::: "memory"); SWRITE(0, SE); __syncthreads();
;     QKT(pA0, pA1, K_lds); partialSM(pA0, pA1, m_reg, mnA, alA, a.C, a.thr);
;     SLOAD(SO, 1); if (SDEPTH == 2 && 2 < NT) SLOAD(SE, 2);
;     SWRITE(1, SO); __syncthreads();
	ds_read_b128 v[0:3], v186 offset:32768
	ds_read_b128 v[4:7], v186 offset:36864
	s_waitcnt vmcnt(3) lgkmcnt(1)
	v_mfma_f32_32x32x16_bf16 v[32:47], v[0:3], v[110:113], 0
	v_or_b32_e32 v0, 32, v96
	v_bitop3_b32 v0, v0, v53, v54 bitop3:0xde
	v_add_u32_e32 v188, 0, v0
	ds_read_b128 v[0:3], v188 offset:32768
	v_and_b32_e32 v8, 0x3fffffc0, v14
	v_lshl_add_u32 v161, v8, 2, 0
	v_lshlrev_b32_e32 v8, 3, v69
	s_waitcnt lgkmcnt(1)
	v_mfma_f32_32x32x16_bf16 v[16:31], v[4:7], v[110:113], 0
	ds_read_b128 v[4:7], v188 offset:36864
	s_mov_b32 s37, s36
	s_mov_b32 s38, s36
	s_mov_b32 s39, s36
	s_mov_b32 s40, s36
	s_mov_b32 s41, s36
	s_mov_b32 s42, s36
	s_waitcnt vmcnt(2) lgkmcnt(1)
	v_mfma_f32_32x32x16_bf16 v[32:47], v[0:3], v[106:109], v[32:47]
	v_or_b32_e32 v0, 64, v96
	v_bitop3_b32 v0, v0, v53, v54 bitop3:0xde
	v_add_u32_e32 v190, 0, v0
	ds_read_b128 v[0:3], v190 offset:32768
	s_mov_b32 s43, s36
	s_mov_b32 s44, s36
	s_mov_b32 s45, s36
	s_waitcnt lgkmcnt(1)
	v_mfma_f32_32x32x16_bf16 v[16:31], v[4:7], v[106:109], v[16:31]
	v_and_b32_e32 v4, 0xc0, v52
	v_lshlrev_b32_e32 v5, 1, v14
	v_and_or_b32 v4, v8, 24, v4
	v_and_b32_e32 v5, 32, v5
	v_and_b32_e32 v6, 0x100, v8
	v_or3_b32 v70, v4, v5, v6
	ds_read_b128 v[4:7], v190 offset:36864
	s_waitcnt vmcnt(1) lgkmcnt(1)
	v_mfma_f32_32x32x16_bf16 v[32:47], v[0:3], v[102:105], v[32:47]
	v_or_b32_e32 v0, 0x60, v96
	v_bitop3_b32 v0, v0, v53, v54 bitop3:0xde
	v_add_u32_e32 v192, 0, v0
	ds_read_b128 v[0:3], v192 offset:32768
	ds_read_b128 v[52:55], v192 offset:36864
	s_mov_b32 s46, s36
	s_mov_b32 s47, s36
	s_waitcnt lgkmcnt(2)
	v_mfma_f32_32x32x16_bf16 v[16:31], v[4:7], v[102:105], v[16:31]
	s_mov_b32 s48, s36
	s_mov_b32 s49, s36
	s_mov_b32 s50, s36
	s_mov_b32 s51, s36
	v_add_u32_e32 v180, s14, v70
	v_lshl_add_u64 v[170:171], s[20:21], 0, v[48:49]
	s_mov_b32 s52, 4
	s_waitcnt vmcnt(0) lgkmcnt(1)
	v_mfma_f32_32x32x16_bf16 v[32:47], v[0:3], v[98:101], v[32:47]
	v_mov_b64_e32 v[0:1], s[36:37]
	v_mov_b64_e32 v[14:15], s[50:51]
	v_mov_b64_e32 v[2:3], s[38:39]
	v_mov_b64_e32 v[4:5], s[40:41]
	v_mov_b64_e32 v[6:7], s[42:43]
	v_mov_b64_e32 v[8:9], s[44:45]
	v_mov_b64_e32 v[10:11], s[46:47]
	s_waitcnt lgkmcnt(0)
	v_mfma_f32_32x32x16_bf16 v[16:31], v[52:55], v[98:101], v[16:31]
	s_nop 2
	v_max_f32_e32 v52, v33, v33
	v_max_f32_e32 v53, v32, v32
	v_max_f32_e32 v52, v53, v52
	v_max3_f32 v52, v52, v34, v35
	v_max3_f32 v52, v52, v36, v37
	v_max3_f32 v52, v52, v38, v39
	v_max3_f32 v52, v52, v40, v41
	v_max3_f32 v52, v52, v42, v43
	v_max3_f32 v52, v52, v44, v45
	v_max3_f32 v52, v52, v46, v47
	v_max3_f32 v52, v52, v16, v17
	v_max3_f32 v71, v52, v18, v19
	v_mov_b64_e32 v[12:13], s[48:49]
	v_lshl_add_u32 v177, v68, 2, v161
	global_load_dwordx4 v[114:117], v[64:65], off
	v_lshl_add_u64 v[64:65], v[168:169], 0, s[88:89]
	v_mad_u64_u32 v[50:51], s[12:13], v64, s9, v[50:51]
	v_mad_i32_i24 v51, v65, s9, v51
	v_lshl_add_u64 v[50:51], v[50:51], 0, v[48:49]
	v_lshl_add_u64 v[64:65], v[166:167], 0, s[90:91]
	global_load_dwordx4 v[118:121], v[50:51], off
	global_load_dwordx4 v[122:125], v[64:65], off
	v_max3_f32 v50, v71, v20, v21
	v_max3_f32 v50, v50, v22, v23
	v_max3_f32 v50, v50, v24, v25
	v_max3_f32 v50, v50, v26, v27
	v_max3_f32 v50, v50, v28, v29
	v_max3_f32 v50, v50, v30, v31
	v_mov_b32_e32 v51, v50
	s_nop 1
	v_permlane32_swap_b32_e32 v50, v51
	v_max_f32_e32 v51, v51, v51
	v_max_f32_e32 v50, v50, v50
	v_max_f32_e32 v50, v50, v51
	v_add_f32_e32 v51, 0x7149f2ca, v50
	v_max_f32_e32 v50, 0xf149f2ca, v50
	v_cmp_ge_f32_e32 vcc, s76, v51
	v_sub_f32_e32 v51, 0xf149f2ca, v50
	v_mul_f32_e32 v51, 0x3e38aa3b, v51
	v_exp_f32_e32 v51, v51
	s_cmp_eq_u64 vcc, exec
	s_cselect_b64 vcc, -1, 0
	v_cndmask_b32_e32 v142, v50, v193, vcc
	v_mul_f32_e32 v50, 0xbe38aa3b, v142
	v_cndmask_b32_e64 v194, v51, 1.0, vcc
	v_mov_b32_e32 v51, v50
	v_fmamk_f32 v32, v32, 0x3e38aa3b, v50
	v_fmamk_f32 v33, v33, 0x3e38aa3b, v50
	v_fmamk_f32 v34, v34, 0x3e38aa3b, v50
	v_fmamk_f32 v35, v35, 0x3e38aa3b, v50
	v_fmamk_f32 v36, v36, 0x3e38aa3b, v50
	v_fmamk_f32 v37, v37, 0x3e38aa3b, v50
	v_fmamk_f32 v38, v38, 0x3e38aa3b, v50
	v_fmamk_f32 v39, v39, 0x3e38aa3b, v50
	v_fmamk_f32 v40, v40, 0x3e38aa3b, v50
	v_fmamk_f32 v41, v41, 0x3e38aa3b, v50
	v_fmamk_f32 v42, v42, 0x3e38aa3b, v50
	v_fmamk_f32 v43, v43, 0x3e38aa3b, v50
	v_fmamk_f32 v44, v44, 0x3e38aa3b, v50
	v_fmamk_f32 v45, v45, 0x3e38aa3b, v50
	v_fmamk_f32 v46, v46, 0x3e38aa3b, v50
	v_fmac_f32_e32 v51, 0x3e38aa3b, v47
	v_exp_f32_e32 v217, v32
	v_exp_f32_e32 v219, v33
	v_exp_f32_e32 v208, v34
	v_exp_f32_e32 v218, v35
	v_exp_f32_e32 v153, v36
	v_exp_f32_e32 v216, v37
	v_exp_f32_e32 v152, v38
	v_exp_f32_e32 v202, v39
	v_exp_f32_e32 v149, v40
	v_exp_f32_e32 v151, v41
	v_exp_f32_e32 v147, v42
	v_exp_f32_e32 v150, v43
	v_exp_f32_e32 v145, v44
	v_exp_f32_e32 v148, v45
	v_exp_f32_e32 v144, v46
	v_exp_f32_e32 v146, v51
	v_pk_fma_f32 v[132:133], v[30:31], s[8:9], v[50:51] op_sel_hi:[1,0,0]
	v_pk_fma_f32 v[134:135], v[28:29], s[8:9], v[50:51] op_sel_hi:[1,0,0]
	v_pk_fma_f32 v[140:141], v[26:27], s[8:9], v[50:51] op_sel_hi:[1,0,0]
	v_pk_fma_f32 v[126:127], v[24:25], s[8:9], v[50:51] op_sel_hi:[1,0,0]
	v_pk_fma_f32 v[128:129], v[22:23], s[8:9], v[50:51] op_sel_hi:[1,0,0]
	v_pk_fma_f32 v[130:131], v[20:21], s[8:9], v[50:51] op_sel_hi:[1,0,0]
	v_pk_fma_f32 v[136:137], v[18:19], s[8:9], v[50:51] op_sel_hi:[1,0,0]
	v_pk_fma_f32 v[138:139], v[16:17], s[8:9], v[50:51] op_sel_hi:[1,0,0]
	s_waitcnt vmcnt(3)
	ds_write_b128 v181, v[240:243] offset:16384
	ds_write_b128 v184, v[244:247] offset:16384
	ds_write_b128 v182, v[248:251] offset:40960
	s_addk_i32 s14, 0x4000
	v_mov_b64_e32 v[30:31], v[14:15]
	v_mov_b64_e32 v[46:47], v[14:15]
	v_mov_b64_e32 v[62:63], v[14:15]
	v_cmp_gt_u32_e64 s[12:13], 32, v69
	v_add_u32_e32 v179, s14, v70
	v_mov_b32_e32 v178, 0
	v_mov_b64_e32 v[28:29], v[12:13]
	v_mov_b64_e32 v[26:27], v[10:11]
	v_mov_b64_e32 v[24:25], v[8:9]
	v_mov_b64_e32 v[22:23], v[6:7]
	v_mov_b64_e32 v[20:21], v[4:5]
	v_mov_b64_e32 v[18:19], v[2:3]
	v_mov_b64_e32 v[16:17], v[0:1]
	v_mov_b64_e32 v[44:45], v[12:13]
	v_mov_b64_e32 v[42:43], v[10:11]
	v_mov_b64_e32 v[40:41], v[8:9]
	v_mov_b64_e32 v[38:39], v[6:7]
	v_mov_b64_e32 v[36:37], v[4:5]
	v_mov_b64_e32 v[34:35], v[2:3]
	v_mov_b64_e32 v[32:33], v[0:1]
	v_mov_b64_e32 v[60:61], v[12:13]
	v_mov_b64_e32 v[58:59], v[10:11]
	v_mov_b64_e32 v[56:57], v[8:9]
	v_mov_b64_e32 v[54:55], v[6:7]
	v_mov_b64_e32 v[52:53], v[4:5]
	v_mov_b64_e32 v[50:51], v[2:3]
	v_mov_b64_e32 v[48:49], v[0:1]
	s_waitcnt lgkmcnt(0)
	s_barrier
